# x8 + dilated attention: PV transposed-V reads double-buffered, drop redundant vmcnt(0) before V ds_writes, V address calc and loads interleaved into QK MFMA chain
# speedup vs baseline: 1.0074x; 1.0017x over previous
.LBB0_88:
	s_waitcnt lgkmcnt(0)
	v_mfma_f32_32x32x16_bf16 v[66:81], v[66:69], v[82:85], 0
	s_xor_b64 s[10:11], s[20:21], -1
	s_andn2_b64 vcc, exec, s[20:21]
	ds_write_b128 v243, v[114:117]
	ds_write_b128 v244, v[118:121] offset:256
	ds_write_b128 v245, v[122:125] offset:2048
	ds_write_b128 v246, v[126:129] offset:2304
	ds_write_b128 v243, v[130:133] offset:4096
	ds_write_b128 v244, v[134:137] offset:4352
	ds_write_b128 v245, v[138:141] offset:6144
	ds_write_b128 v246, v[142:145] offset:6400
	s_cbranch_vccnz .Ldil_nov
	v_mfma_f32_32x32x16_bf16 v[66:81], v[170:173], v[86:89], v[66:81]
	v_mul_lo_u32 v64, s44, v221
	v_add_u32_e32 v116, s43, v64
	v_med3_i32 v64, v116, 0, v232
	s_lshl_b32 s20, s44, 2
	v_mul_u32_u24_e32 v64, 0x3000, v64
	v_add_u32_e32 v122, s20, v116
	v_lshl_add_u64 v[114:115], v[202:203], 0, v[64:65]
	v_mfma_f32_32x32x16_bf16 v[66:81], v[158:161], v[90:93], v[66:81]
	v_med3_i32 v64, v122, 0, v232
	v_mul_u32_u24_e32 v64, 0x3000, v64
	v_add_u32_e32 v124, s20, v122
	v_lshl_add_u64 v[118:119], v[202:203], 0, v[64:65]
	v_med3_i32 v64, v124, 0, v232
	v_mul_u32_u24_e32 v64, 0x3000, v64
	v_add_u32_e32 v130, s20, v124
	v_mfma_f32_32x32x16_bf16 v[66:81], v[162:165], v[94:97], v[66:81]
	v_lshl_add_u64 v[122:123], v[202:203], 0, v[64:65]
	v_med3_i32 v64, v130, 0, v232
	v_mul_u32_u24_e32 v64, 0x3000, v64
	v_add_u32_e32 v132, s20, v130
	v_lshl_add_u64 v[126:127], v[202:203], 0, v[64:65]
	v_med3_i32 v64, v132, 0, v232
	v_mul_u32_u24_e32 v64, 0x3000, v64
	v_mfma_f32_32x32x16_bf16 v[66:81], v[154:157], v[98:101], v[66:81]
	v_add_u32_e32 v138, s20, v132
	v_lshl_add_u64 v[130:131], v[202:203], 0, v[64:65]
	v_med3_i32 v64, v138, 0, v232
	v_mul_u32_u24_e32 v64, 0x3000, v64
	v_add_u32_e32 v140, s20, v138
	v_lshl_add_u64 v[134:135], v[202:203], 0, v[64:65]
	v_med3_i32 v64, v140, 0, v232
	v_mfma_f32_32x32x16_bf16 v[66:81], v[166:169], v[102:105], v[66:81]
	v_mul_u32_u24_e32 v64, 0x3000, v64
	v_lshl_add_u64 v[138:139], v[202:203], 0, v[64:65]
	v_add_u32_e32 v64, s20, v140
	v_med3_i32 v64, v64, 0, v232
	v_mul_u32_u24_e32 v64, 0x3000, v64
	v_lshl_add_u64 v[142:143], v[202:203], 0, v[64:65]
	v_mfma_f32_32x32x16_bf16 v[66:81], v[150:153], v[106:109], v[66:81]
	global_load_dwordx4 v[114:117], v[114:115], off
	s_nop 0
	global_load_dwordx4 v[118:121], v[118:119], off
	s_nop 0
	global_load_dwordx4 v[122:125], v[122:123], off
	s_nop 0
	global_load_dwordx4 v[126:129], v[126:127], off
	s_nop 0
	v_mfma_f32_32x32x16_bf16 v[66:81], v[146:149], v[110:113], v[66:81]
	global_load_dwordx4 v[130:133], v[130:131], off
	s_nop 0
	global_load_dwordx4 v[134:137], v[134:135], off
	s_nop 0
	global_load_dwordx4 v[138:141], v[138:139], off
	s_nop 0
	global_load_dwordx4 v[142:145], v[142:143], off
	s_branch .LBB0_90
.Ldil_nov:
	v_mfma_f32_32x32x16_bf16 v[66:81], v[170:173], v[86:89], v[66:81]
	v_mfma_f32_32x32x16_bf16 v[66:81], v[158:161], v[90:93], v[66:81]
	v_mfma_f32_32x32x16_bf16 v[66:81], v[162:165], v[94:97], v[66:81]
	v_mfma_f32_32x32x16_bf16 v[66:81], v[154:157], v[98:101], v[66:81]
	v_mfma_f32_32x32x16_bf16 v[66:81], v[166:169], v[102:105], v[66:81]
	v_mfma_f32_32x32x16_bf16 v[66:81], v[150:153], v[106:109], v[66:81]
	v_mfma_f32_32x32x16_bf16 v[66:81], v[146:149], v[110:113], v[66:81]
	s_nop 3
.LBB0_90:
	s_cmp_eq_u32 s42, 0
	s_cselect_b64 vcc, -1, 0
	s_cmp_eq_u32 s42, 1
	s_cselect_b64 s[20:21], -1, 0
	s_cmp_lg_u32 s42, 2
	s_mulk_i32 s42, 0x600
	v_cndmask_b32_e64 v64, v220, v195, s[20:21]
	s_cselect_b64 s[20:21], -1, 0
	v_sub_u32_e32 v150, v249, v225
	s_add_i32 s42, s42, 0x10000
	v_lshl_add_u32 v151, v150, 2, s42
	ds_read2_b32 v[146:147], v151 offset0:127 offset1:128
	ds_read2_b32 v[148:149], v151 offset0:125 offset1:126
	v_cndmask_b32_e32 v64, v64, v218, vcc
	v_cmp_eq_u32_e32 vcc, s41, v224
	s_or_b64 s[20:21], s[20:21], vcc
	v_min_i32_e32 v64, 0x80, v64
	v_cndmask_b32_e64 v152, v235, -v217, s[20:21]
	s_waitcnt lgkmcnt(1)
	v_fmamk_f32 v66, v66, 0x3e0293ee, v147
	v_add_f32_e32 v66, v152, v66
	v_cmp_le_u32_e32 vcc, v150, v64
	v_fmac_f32_e32 v146, 0x3e0293ee, v67
	v_add_u32_e32 v67, -1, v150
	v_cndmask_b32_e32 v147, v235, v66, vcc
	v_add_f32_e32 v66, v152, v146
	v_cmp_le_u32_e32 vcc, v67, v64
	s_nop 1
	v_cndmask_b32_e32 v146, v235, v66, vcc
	ds_read2_b32 v[66:67], v151 offset0:119 offset1:120
	s_waitcnt lgkmcnt(1)
	v_fmamk_f32 v68, v68, 0x3e0293ee, v149
	v_add_u32_e32 v149, -2, v150
	v_add_f32_e32 v68, v152, v68
	v_cmp_le_u32_e32 vcc, v149, v64
	v_fmac_f32_e32 v148, 0x3e0293ee, v69
	v_add_u32_e32 v69, -3, v150
	v_cndmask_b32_e32 v149, v235, v68, vcc
	v_add_f32_e32 v68, v152, v148
	v_cmp_le_u32_e32 vcc, v69, v64
	s_nop 1
	v_cndmask_b32_e32 v148, v235, v68, vcc
	ds_read2_b32 v[68:69], v151 offset0:117 offset1:118
	s_waitcnt lgkmcnt(1)
	v_fmamk_f32 v67, v70, 0x3e0293ee, v67
	v_add_u32_e32 v70, -8, v150
	v_add_f32_e32 v67, v152, v67
	v_cmp_le_u32_e32 vcc, v70, v64
	v_fmac_f32_e32 v66, 0x3e0293ee, v71
	v_add_f32_e32 v66, v152, v66
	v_cndmask_b32_e32 v70, v235, v67, vcc
	v_add_u32_e32 v67, -9, v150
	v_cmp_le_u32_e32 vcc, v67, v64
	v_add_u32_e32 v67, -10, v150
	s_waitcnt lgkmcnt(0)
	v_fmac_f32_e32 v68, 0x3e0293ee, v73
	v_cndmask_b32_e32 v71, v235, v66, vcc
	v_fmamk_f32 v66, v72, 0x3e0293ee, v69
	v_add_f32_e32 v66, v152, v66
	v_cmp_le_u32_e32 vcc, v67, v64
	v_add_u32_e32 v69, -11, v150
	v_add_f32_e32 v68, v152, v68
	v_cndmask_b32_e32 v72, v235, v66, vcc
	ds_read2_b32 v[66:67], v151 offset0:111 offset1:112
	v_cmp_le_u32_e32 vcc, v69, v64
	v_exp_f32_e32 v70, v70
	v_exp_f32_e32 v71, v71
	v_cndmask_b32_e32 v73, v235, v68, vcc
	ds_read2_b32 v[68:69], v151 offset0:109 offset1:110
	s_waitcnt lgkmcnt(1)
	v_fmamk_f32 v67, v74, 0x3e0293ee, v67
	v_add_u32_e32 v74, -16, v150
	v_add_f32_e32 v67, v152, v67
	v_cmp_le_u32_e32 vcc, v74, v64
	v_fmac_f32_e32 v66, 0x3e0293ee, v75
	v_add_f32_e32 v66, v152, v66
	v_cndmask_b32_e32 v74, v235, v67, vcc
	v_subrev_u32_e32 v67, 17, v150
	v_cmp_le_u32_e32 vcc, v67, v64
	v_exp_f32_e32 v72, v72
	v_exp_f32_e32 v73, v73
	v_cndmask_b32_e32 v75, v235, v66, vcc
	ds_read2_b32 v[66:67], v151 offset0:103 offset1:104
	s_waitcnt lgkmcnt(1)
	v_fmamk_f32 v69, v76, 0x3e0293ee, v69
	v_subrev_u32_e32 v76, 18, v150
	v_add_f32_e32 v69, v152, v69
	v_cmp_le_u32_e32 vcc, v76, v64
	v_fmac_f32_e32 v68, 0x3e0293ee, v77
	v_add_f32_e32 v68, v152, v68
	v_cndmask_b32_e32 v76, v235, v69, vcc
	v_subrev_u32_e32 v69, 19, v150
	v_cmp_le_u32_e32 vcc, v69, v64
	v_exp_f32_e32 v74, v74
	v_exp_f32_e32 v75, v75
	v_cndmask_b32_e32 v77, v235, v68, vcc
	ds_read2_b32 v[68:69], v151 offset0:101 offset1:102
	s_waitcnt lgkmcnt(1)
	v_fmamk_f32 v67, v78, 0x3e0293ee, v67
	v_subrev_u32_e32 v78, 24, v150
	v_add_f32_e32 v67, v152, v67
	v_cmp_le_u32_e32 vcc, v78, v64
	v_fmac_f32_e32 v66, 0x3e0293ee, v79
	v_subrev_u32_e32 v78, 25, v150
	v_cndmask_b32_e32 v67, v235, v67, vcc
	v_add_f32_e32 v66, v152, v66
	v_cmp_le_u32_e32 vcc, v78, v64
	s_waitcnt lgkmcnt(0)
	v_fmamk_f32 v69, v80, 0x3e0293ee, v69
	v_subrev_u32_e32 v78, 26, v150
	v_cndmask_b32_e32 v66, v235, v66, vcc
	v_add_f32_e32 v69, v152, v69
	v_cmp_le_u32_e32 vcc, v78, v64
	v_fmac_f32_e32 v68, 0x3e0293ee, v81
	v_subrev_u32_e32 v78, 27, v150
	v_cndmask_b32_e32 v69, v235, v69, vcc
	v_add_f32_e32 v68, v152, v68
	v_cmp_le_u32_e32 vcc, v78, v64
	v_exp_f32_e32 v78, v146
	v_exp_f32_e32 v79, v149
	v_cndmask_b32_e32 v64, v235, v68, vcc
	v_exp_f32_e32 v68, v147
	v_exp_f32_e32 v80, v148
	v_exp_f32_e32 v76, v76
	v_exp_f32_e32 v77, v77
	v_add_f32_e32 v81, 0, v68
	v_add_f32_e32 v81, v78, v81
	v_add_f32_e32 v81, v79, v81
	v_add_f32_e32 v81, v80, v81
	v_add_f32_e32 v81, v70, v81
	v_add_f32_e32 v81, v71, v81
	v_add_f32_e32 v81, v72, v81
	v_add_f32_e32 v81, v73, v81
	v_add_f32_e32 v81, v74, v81
	v_exp_f32_e32 v146, v67
	v_add_f32_e32 v81, v75, v81
	v_exp_f32_e32 v147, v66
	v_add_f32_e32 v81, v76, v81
	v_exp_f32_e32 v148, v69
	v_add_f32_e32 v81, v77, v81
	v_exp_f32_e32 v64, v64
	v_add_f32_e32 v66, v146, v81
	v_add_f32_e32 v66, v147, v66
	v_add_f32_e32 v66, v148, v66
	v_add_f32_e32 v66, v64, v66
	v_add_f32_e32 v216, v216, v66
	v_cvt_pk_bf16_f32 v66, v68, v78
	v_cvt_pk_bf16_f32 v67, v79, v80
	v_cvt_pk_bf16_f32 v68, v70, v71
	v_cvt_pk_bf16_f32 v69, v72, v73
	v_cvt_pk_bf16_f32 v70, v74, v75
	v_cvt_pk_bf16_f32 v71, v76, v77
	v_cvt_pk_bf16_f32 v72, v146, v147
	v_cvt_pk_bf16_f32 v73, v148, v64
	ds_read_b64_tr_b16 v[74:75], v247
	ds_read_b64_tr_b16 v[78:79], v247 offset:4096
	ds_read_b64_tr_b16 v[146:147], v247 offset:4608
	ds_read_b64_tr_b16 v[150:151], v247 offset:512
	ds_read_b64_tr_b16 v[76:77], v248 offset:2048
	ds_read_b64_tr_b16 v[80:81], v248 offset:6144
	ds_read_b64_tr_b16 v[148:149], v248 offset:6656
	ds_read_b64_tr_b16 v[152:153], v248 offset:2560
	ds_read_b64_tr_b16 v[154:155], v247 offset:1024
	ds_read_b64_tr_b16 v[158:159], v247 offset:5120
	ds_read_b64_tr_b16 v[162:163], v247 offset:5632
	ds_read_b64_tr_b16 v[166:167], v247 offset:1536
	ds_read_b64_tr_b16 v[156:157], v248 offset:3072
	ds_read_b64_tr_b16 v[160:161], v248 offset:7168
	ds_read_b64_tr_b16 v[164:165], v248 offset:7680
	ds_read_b64_tr_b16 v[168:169], v248 offset:3584
	s_waitcnt lgkmcnt(8)
	v_mfma_f32_32x32x16_bf16 v[48:63], v[74:77], v[66:69], v[48:63]
	v_mfma_f32_32x32x16_bf16 v[32:47], v[150:153], v[66:69], v[32:47]
	v_mfma_f32_32x32x16_bf16 v[48:63], v[78:81], v[70:73], v[48:63]
	v_mfma_f32_32x32x16_bf16 v[32:47], v[146:149], v[70:73], v[32:47]
	s_waitcnt lgkmcnt(0)
	v_mfma_f32_32x32x16_bf16 v[16:31], v[154:157], v[66:69], v[16:31]
	v_mfma_f32_32x32x16_bf16 v[0:15], v[166:169], v[66:69], v[0:15]
	v_mfma_f32_32x32x16_bf16 v[16:31], v[158:161], v[70:73], v[16:31]
	v_mfma_f32_32x32x16_bf16 v[0:15], v[162:165], v[70:73], v[0:15]
	s_andn2_b64 vcc, exec, s[10:11]
	s_cbranch_vccz .LBB0_149
	s_mov_b32 s41, s24
	s_mov_b32 s42, s25
	v_mov_b32_e32 v249, v250
	s_branch .LBB0_69
